# pipelined LDS reads in GEMM1 and merge-gate K-loops (counted lgkmcnt, saddr DMA), batched NA bias loads
# speedup vs baseline: 1.0209x; 1.0209x over previous
.LBB0_60:
.LBB0_61:
	v_readfirstlane_b32 s7, v98
	s_mul_i32 s69, s68, 0xc000
	s_add_i32 s8, s68, -1
	s_cmp_eq_u32 s68, 0
	s_cselect_b32 s8, 2, s8
	s_mul_i32 s8, s8, 0xc000
	s_add_i32 s6, s8, s7
	v_add3_u32 v238, s69, v101, v100
	v_add3_u32 v239, s69, v99, v100
	ds_read_b128 v[132:135], v238 offset:0
	ds_read_b128 v[116:119], v239 offset:32768
	ds_read_b128 v[120:123], v239 offset:34816
	ds_read_b128 v[136:139], v238 offset:2048
	ds_read_b128 v[140:143], v238 offset:4096
	ds_read_b128 v[144:147], v238 offset:6144
	ds_read_b128 v[214:217], v238 offset:8192
	ds_read_b128 v[218:221], v238 offset:10240
.Lgg_loop:
	s_waitcnt lgkmcnt(5)
	v_mfma_f32_16x16x32_bf16 v[70:73], v[132:135], v[116:119], v[70:73]
	v_mfma_f32_16x16x32_bf16 v[38:41], v[132:135], v[120:123], v[38:41]
	ds_read_b128 v[222:225], v238 offset:12288
	s_cmp_gt_u32 s67, 13
	s_cbranch_scc1 .Lgg_nodma0
	v_lshl_add_u64 v[240:241], v[96:97], 0, s[46:47]
	s_add_i32 m0, s6, 0x0
	s_nop 0
	global_load_lds_dwordx4 v[240:241], off
.Lgg_nodma0:
	s_waitcnt lgkmcnt(5)
	v_mfma_f32_16x16x32_bf16 v[62:65], v[136:139], v[116:119], v[62:65]
	v_mfma_f32_16x16x32_bf16 v[30:33], v[136:139], v[120:123], v[30:33]
	ds_read_b128 v[234:237], v238 offset:14336
	s_cmp_gt_u32 s67, 13
	s_cbranch_scc1 .Lgg_nodma1
	v_lshl_add_u64 v[240:241], v[94:95], 0, s[46:47]
	s_add_i32 m0, s6, 0x8000
	s_nop 0
	global_load_lds_dwordx4 v[240:241], off
.Lgg_nodma1:
	s_waitcnt lgkmcnt(5)
	v_mfma_f32_16x16x32_bf16 v[58:61], v[140:143], v[116:119], v[58:61]
	v_mfma_f32_16x16x32_bf16 v[22:25], v[140:143], v[120:123], v[22:25]
	ds_read_b128 v[132:135], v238 offset:1024
	ds_read_b128 v[124:127], v239 offset:33792
	s_cmp_gt_u32 s67, 13
	s_cbranch_scc1 .Lgg_nodma2
	v_lshl_add_u64 v[240:241], v[92:93], 0, s[46:47]
	s_add_i32 m0, s6, 0x2000
	s_nop 0
	global_load_lds_dwordx4 v[240:241], off
.Lgg_nodma2:
	s_waitcnt lgkmcnt(6)
	v_mfma_f32_16x16x32_bf16 v[50:53], v[144:147], v[116:119], v[50:53]
	v_mfma_f32_16x16x32_bf16 v[18:21], v[144:147], v[120:123], v[18:21]
	ds_read_b128 v[136:139], v238 offset:3072
	ds_read_b128 v[128:131], v239 offset:35840
	s_cmp_gt_u32 s67, 13
	s_cbranch_scc1 .Lgg_nodma3
	v_lshl_add_u64 v[240:241], v[90:91], 0, s[46:47]
	s_add_i32 m0, s6, 0xa000
	s_nop 0
	global_load_lds_dwordx4 v[240:241], off
.Lgg_nodma3:
	s_waitcnt lgkmcnt(7)
	v_mfma_f32_16x16x32_bf16 v[46:49], v[214:217], v[116:119], v[46:49]
	v_mfma_f32_16x16x32_bf16 v[14:17], v[214:217], v[120:123], v[14:17]
	ds_read_b128 v[140:143], v238 offset:5120
	s_cmp_gt_u32 s67, 13
	s_cbranch_scc1 .Lgg_nodma4
	v_lshl_add_u64 v[240:241], v[88:89], 0, s[46:47]
	s_add_i32 m0, s6, 0x4000
	s_nop 0
	global_load_lds_dwordx4 v[240:241], off
.Lgg_nodma4:
	s_waitcnt lgkmcnt(7)
	v_mfma_f32_16x16x32_bf16 v[42:45], v[218:221], v[116:119], v[42:45]
	v_mfma_f32_16x16x32_bf16 v[10:13], v[218:221], v[120:123], v[10:13]
	ds_read_b128 v[144:147], v238 offset:7168
	s_cmp_gt_u32 s67, 13
	s_cbranch_scc1 .Lgg_nodma5
	v_lshl_add_u64 v[240:241], v[86:87], 0, s[46:47]
	s_add_i32 m0, s6, 0x6000
	s_nop 0
	global_load_lds_dwordx4 v[240:241], off
.Lgg_nodma5:
	s_waitcnt lgkmcnt(7)
	v_mfma_f32_16x16x32_bf16 v[34:37], v[222:225], v[116:119], v[34:37]
	v_mfma_f32_16x16x32_bf16 v[6:9], v[222:225], v[120:123], v[6:9]
	ds_read_b128 v[214:217], v238 offset:9216
	s_waitcnt lgkmcnt(7)
	v_mfma_f32_16x16x32_bf16 v[26:29], v[234:237], v[116:119], v[26:29]
	v_mfma_f32_16x16x32_bf16 v[2:5], v[234:237], v[120:123], v[2:5]
	ds_read_b128 v[218:221], v238 offset:11264
	s_waitcnt lgkmcnt(4)
	v_mfma_f32_16x16x32_bf16 v[70:73], v[132:135], v[124:127], v[70:73]
	v_mfma_f32_16x16x32_bf16 v[38:41], v[132:135], v[128:131], v[38:41]
	ds_read_b128 v[222:225], v238 offset:13312
	v_mfma_f32_16x16x32_bf16 v[62:65], v[136:139], v[124:127], v[62:65]
	v_mfma_f32_16x16x32_bf16 v[30:33], v[136:139], v[128:131], v[30:33]
	ds_read_b128 v[234:237], v238 offset:15360
	s_waitcnt lgkmcnt(5)
	v_mfma_f32_16x16x32_bf16 v[58:61], v[140:143], v[124:127], v[58:61]
	v_mfma_f32_16x16x32_bf16 v[22:25], v[140:143], v[128:131], v[22:25]
	s_waitcnt lgkmcnt(4)
	v_mfma_f32_16x16x32_bf16 v[50:53], v[144:147], v[124:127], v[50:53]
	v_mfma_f32_16x16x32_bf16 v[18:21], v[144:147], v[128:131], v[18:21]
	s_waitcnt lgkmcnt(3)
	v_mfma_f32_16x16x32_bf16 v[46:49], v[214:217], v[124:127], v[46:49]
	v_mfma_f32_16x16x32_bf16 v[14:17], v[214:217], v[128:131], v[14:17]
	s_waitcnt lgkmcnt(2)
	v_mfma_f32_16x16x32_bf16 v[42:45], v[218:221], v[124:127], v[42:45]
	v_mfma_f32_16x16x32_bf16 v[10:13], v[218:221], v[128:131], v[10:13]
	s_waitcnt lgkmcnt(1)
	v_mfma_f32_16x16x32_bf16 v[34:37], v[222:225], v[124:127], v[34:37]
	v_mfma_f32_16x16x32_bf16 v[6:9], v[222:225], v[128:131], v[6:9]
	s_waitcnt lgkmcnt(0)
	s_cmp_gt_u32 s67, 13
	s_cbranch_scc1 .Lgg_w0
	s_waitcnt vmcnt(6)
	s_branch .Lgg_wd

.Lgg_wd:
	s_barrier
	s_add_i32 s67, s67, 1
	s_add_u32 s46, s46, 0x80
	s_addc_u32 s47, s47, 0
	s_add_i32 s9, s68, 1
	s_cmp_lg_u32 s68, 2
	s_cselect_b32 s68, s9, 0
	s_cmpk_eq_i32 s46, 0x800
	s_cbranch_scc1 .Lgg_tail
	s_mul_i32 s69, s68, 0xc000
	s_add_i32 s8, s68, -1
	s_cmp_eq_u32 s68, 0
	s_cselect_b32 s8, 2, s8
	s_mul_i32 s8, s8, 0xc000
	s_add_i32 s6, s8, s7
	v_add3_u32 v238, s69, v101, v100
	v_add3_u32 v239, s69, v99, v100
	ds_read_b128 v[132:135], v238 offset:0
	ds_read_b128 v[116:119], v239 offset:32768
	ds_read_b128 v[120:123], v239 offset:34816
	ds_read_b128 v[136:139], v238 offset:2048
	ds_read_b128 v[140:143], v238 offset:4096
	ds_read_b128 v[144:147], v238 offset:6144
	ds_read_b128 v[214:217], v238 offset:8192
	ds_read_b128 v[218:221], v238 offset:10240
	v_mfma_f32_16x16x32_bf16 v[26:29], v[234:237], v[124:127], v[26:29]
	v_mfma_f32_16x16x32_bf16 v[2:5], v[234:237], v[128:131], v[2:5]
	s_branch .Lgg_loop
.Lgg_tail:
	v_mfma_f32_16x16x32_bf16 v[26:29], v[234:237], v[124:127], v[26:29]
	v_mfma_f32_16x16x32_bf16 v[2:5], v[234:237], v[128:131], v[2:5]

.LBB0_159:
	s_cmp_gt_u32 s85, 7
	v_add_u32_e32 v0, s85, v193
	s_cselect_b64 s[6:7], -1, 0
	s_cmp_lt_u32 s85, 8
	v_cmp_ge_u32_e32 vcc, v0, v188
	v_cmp_lt_u32_e64 s[74:75], v0, v189
	s_cselect_b64 s[76:77], -1, 0
	s_and_b64 s[74:75], vcc, s[74:75]
	s_or_b64 s[76:77], s[76:77], s[74:75]
	s_and_saveexec_b64 s[74:75], s[76:77]
	s_cbranch_execz .LBB0_149
	s_bitcmp1_b32 s85, 0
	s_cselect_b32 s76, 0x4800, 0
	v_add_u32_e32 v195, s76, v190
	s_waitcnt vmcnt(2)
	ds_read_b128 v[50:53], v195
	ds_read_b128 v[146:149], v195 offset:4608
	s_andn2_b64 vcc, exec, s[6:7]
	s_waitcnt lgkmcnt(1)
	v_mfma_f32_32x32x16_bf16 v[66:81], v[50:53], v[90:93], v[34:49]
	ds_read_b128 v[50:53], v195 offset:32
	s_waitcnt lgkmcnt(0)
	v_mfma_f32_32x32x16_bf16 v[66:81], v[50:53], v[82:85], v[66:81]
	ds_read_b128 v[50:53], v195 offset:64
	s_waitcnt lgkmcnt(0)
	v_mfma_f32_32x32x16_bf16 v[66:81], v[50:53], v[86:89], v[66:81]
	ds_read_b128 v[50:53], v195 offset:96
	s_waitcnt lgkmcnt(0)
	v_mfma_f32_32x32x16_bf16 v[66:81], v[50:53], v[94:97], v[66:81]
	s_waitcnt vmcnt(0)
	v_mov_b64_e32 v[64:65], v[48:49]
	v_mov_b64_e32 v[62:63], v[46:47]
	v_mov_b64_e32 v[60:61], v[44:45]
	v_mov_b64_e32 v[58:59], v[42:43]
	v_mov_b64_e32 v[56:57], v[40:41]
	v_mov_b64_e32 v[54:55], v[38:39]
	v_mov_b64_e32 v[52:53], v[36:37]
	v_mov_b64_e32 v[50:51], v[34:35]
	s_nop 1
	v_mfma_f32_32x32x16_bf16 v[50:65], v[146:149], v[90:93], v[50:65]
	ds_read_b128 v[146:149], v195 offset:4640
	s_waitcnt lgkmcnt(0)
	v_mfma_f32_32x32x16_bf16 v[50:65], v[146:149], v[82:85], v[50:65]
	ds_read_b128 v[146:149], v195 offset:4672
	s_waitcnt lgkmcnt(0)
	v_mfma_f32_32x32x16_bf16 v[50:65], v[146:149], v[86:89], v[50:65]
	ds_read_b128 v[146:149], v195 offset:4704
	s_waitcnt lgkmcnt(0)
	v_mfma_f32_32x32x16_bf16 v[50:65], v[146:149], v[94:97], v[50:65]
	s_cbranch_vccnz .LBB0_226
	v_mov_b32_e32 v0, 0xf149f2ca
	ds_read2_b32 v[146:147], v192 offset0:0 offset1:1
	ds_read2_b32 v[148:149], v192 offset0:2 offset1:3
	ds_read2_b32 v[150:151], v192 offset0:8 offset1:9
	ds_read2_b32 v[152:153], v192 offset0:10 offset1:11
	ds_read2_b32 v[154:155], v192 offset0:16 offset1:17
	ds_read2_b32 v[156:157], v192 offset0:18 offset1:19
	ds_read2_b32 v[158:159], v192 offset0:24 offset1:25
	ds_read2_b32 v[160:161], v192 offset0:26 offset1:27
	ds_read2_b32 v[162:163], v192 offset0:32 offset1:33
	ds_read2_b32 v[164:165], v192 offset0:34 offset1:35
	ds_read2_b32 v[166:167], v192 offset0:40 offset1:41
	ds_read2_b32 v[168:169], v192 offset0:42 offset1:43
	ds_read2_b32 v[170:171], v192 offset0:48 offset1:49
	ds_read2_b32 v[172:173], v192 offset0:50 offset1:51
	ds_read2_b32 v[174:175], v192 offset0:56 offset1:57
	ds_read2_b32 v[176:177], v192 offset0:58 offset1:59
	s_waitcnt lgkmcnt(15)
	v_add_f32_e32 v146, v66, v146
	v_cndmask_b32_e64 v146, v0, v146, s[8:9]
	v_add_f32_e32 v147, v67, v147
	v_cndmask_b32_e64 v147, v0, v147, s[10:11]
	s_waitcnt lgkmcnt(14)
	v_add_f32_e32 v148, v68, v148
	v_cndmask_b32_e64 v148, v0, v148, s[12:13]
	v_add_f32_e32 v149, v69, v149
	v_cndmask_b32_e64 v149, v0, v149, s[14:15]
	s_waitcnt lgkmcnt(13)
	v_add_f32_e32 v150, v70, v150
	v_cndmask_b32_e64 v150, v0, v150, s[16:17]
	v_add_f32_e32 v151, v71, v151
	v_cndmask_b32_e64 v151, v0, v151, s[18:19]
	s_waitcnt lgkmcnt(12)
	v_add_f32_e32 v152, v72, v152
	v_cndmask_b32_e64 v152, v0, v152, s[20:21]
	v_add_f32_e32 v153, v73, v153
	v_cndmask_b32_e64 v153, v0, v153, s[22:23]
	s_waitcnt lgkmcnt(11)
	v_add_f32_e32 v154, v74, v154
	v_cndmask_b32_e64 v154, v0, v154, s[24:25]
	v_add_f32_e32 v155, v75, v155
	v_cndmask_b32_e64 v155, v0, v155, s[26:27]
	s_waitcnt lgkmcnt(10)
	v_add_f32_e32 v156, v76, v156
	v_cndmask_b32_e64 v156, v0, v156, s[28:29]
	v_add_f32_e32 v157, v77, v157
	v_cndmask_b32_e64 v157, v0, v157, s[30:31]
	s_waitcnt lgkmcnt(9)
	v_add_f32_e32 v158, v78, v158
	v_cndmask_b32_e64 v158, v0, v158, s[34:35]
	v_add_f32_e32 v159, v79, v159
	v_cndmask_b32_e64 v159, v0, v159, s[36:37]
	s_waitcnt lgkmcnt(8)
	v_add_f32_e32 v160, v80, v160
	v_cndmask_b32_e64 v160, v0, v160, s[38:39]
	v_add_f32_e32 v161, v81, v161
	v_cndmask_b32_e64 v161, v0, v161, s[40:41]
	s_waitcnt lgkmcnt(7)
	v_add_f32_e32 v162, v50, v162
	v_cndmask_b32_e64 v162, v0, v162, s[42:43]
	v_add_f32_e32 v163, v51, v163
	v_cndmask_b32_e64 v163, v0, v163, s[44:45]
	s_waitcnt lgkmcnt(6)
	v_add_f32_e32 v164, v52, v164
	v_cndmask_b32_e64 v164, v0, v164, s[46:47]
	v_add_f32_e32 v165, v53, v165
	v_cndmask_b32_e64 v165, v0, v165, s[48:49]
	s_waitcnt lgkmcnt(5)
	v_add_f32_e32 v166, v54, v166
	v_cndmask_b32_e64 v166, v0, v166, s[50:51]
	v_add_f32_e32 v167, v55, v167
	v_cndmask_b32_e64 v167, v0, v167, s[52:53]
	s_waitcnt lgkmcnt(4)
	v_add_f32_e32 v168, v56, v168
	v_cndmask_b32_e64 v168, v0, v168, s[54:55]
	v_add_f32_e32 v169, v57, v169
	v_cndmask_b32_e64 v169, v0, v169, s[56:57]
	s_waitcnt lgkmcnt(3)
	v_add_f32_e32 v170, v58, v170
	v_cndmask_b32_e64 v170, v0, v170, s[58:59]
	v_add_f32_e32 v171, v59, v171
	v_cndmask_b32_e64 v171, v0, v171, s[60:61]
	s_waitcnt lgkmcnt(2)
	v_add_f32_e32 v172, v60, v172
	v_cndmask_b32_e64 v172, v0, v172, s[62:63]
	v_add_f32_e32 v173, v61, v173
	v_cndmask_b32_e64 v173, v0, v173, s[64:65]
	s_waitcnt lgkmcnt(1)
	v_add_f32_e32 v174, v62, v174
	v_cndmask_b32_e64 v174, v0, v174, s[66:67]
	v_add_f32_e32 v175, v63, v175
	v_cndmask_b32_e64 v175, v0, v175, s[68:69]
	s_waitcnt lgkmcnt(0)
	v_add_f32_e32 v176, v64, v176
	v_cndmask_b32_e64 v176, v0, v176, s[70:71]
	v_add_f32_e32 v177, v65, v177
	v_cndmask_b32_e64 v177, v0, v177, s[72:73]
	s_branch .LBB0_227

.LBB0_328:
.LBB0_329:
	v_readfirstlane_b32 s8, v212
	v_readfirstlane_b32 s9, v213
	v_readfirstlane_b32 s14, v210
	v_readfirstlane_b32 s15, v211
	v_readfirstlane_b32 s18, v165
	s_nop 1
	v_subrev_u32_e32 v173, s8, v212
	v_subrev_u32_e32 v175, s8, v208
	v_subrev_u32_e32 v177, s8, v204
	v_subrev_u32_e32 v179, s8, v200
	v_subrev_u32_e32 v181, s14, v210
	v_subrev_u32_e32 v183, s14, v206
	v_subrev_u32_e32 v185, s14, v202
	v_subrev_u32_e32 v241, s14, v198
	s_and_b32 s16, s5, 0x10000
	v_add3_u32 v187, s16, v171, v169
	v_add3_u32 v0, s16, v167, v169
	ds_read_b128 v[146:149], v187 offset:0
	ds_read_b128 v[130:133], v0 offset:32768
	ds_read_b128 v[134:137], v0 offset:34816
	ds_read_b128 v[138:141], v0 offset:36864
	ds_read_b128 v[142:145], v0 offset:38912
	ds_read_b128 v[150:153], v187 offset:2048
	ds_read_b128 v[154:157], v187 offset:4096
	s_xor_b32 s17, s16, 0x10000
	s_add_i32 s17, s17, s18
.Lg1_loop:
	s_waitcnt lgkmcnt(5)
	v_mfma_f32_16x16x32_bf16 v[126:129], v[146:149], v[130:133], v[126:129]
	s_waitcnt lgkmcnt(4)
	v_mfma_f32_16x16x32_bf16 v[122:125], v[146:149], v[134:137], v[122:125]
	s_waitcnt lgkmcnt(3)
	v_mfma_f32_16x16x32_bf16 v[118:121], v[146:149], v[138:141], v[118:121]
	s_waitcnt lgkmcnt(2)
	v_mfma_f32_16x16x32_bf16 v[114:117], v[146:149], v[142:145], v[114:117]
	ds_read_b128 v[242:245], v187 offset:6144
	s_cmpk_eq_i32 s10, 0x780
	s_cbranch_scc1 .Lg1_nodma0
	s_add_i32 m0, s17, 0x0
	s_nop 0
	global_load_lds_dwordx4 v173, s[8:9]
.Lg1_nodma0:
	s_waitcnt lgkmcnt(2)
	v_mfma_f32_16x16x32_bf16 v[110:113], v[150:153], v[130:133], v[110:113]
	v_mfma_f32_16x16x32_bf16 v[106:109], v[150:153], v[134:137], v[106:109]
	v_mfma_f32_16x16x32_bf16 v[102:105], v[150:153], v[138:141], v[102:105]
	v_mfma_f32_16x16x32_bf16 v[98:101], v[150:153], v[142:145], v[98:101]
	ds_read_b128 v[146:149], v187 offset:8192
	s_cmpk_eq_i32 s10, 0x780
	s_cbranch_scc1 .Lg1_nodma1
	s_add_i32 m0, s17, 0x8000
	s_nop 0
	global_load_lds_dwordx4 v181, s[14:15]
.Lg1_nodma1:
	s_waitcnt lgkmcnt(2)
	v_mfma_f32_16x16x32_bf16 v[94:97], v[154:157], v[130:133], v[94:97]
	v_mfma_f32_16x16x32_bf16 v[90:93], v[154:157], v[134:137], v[90:93]
	v_mfma_f32_16x16x32_bf16 v[82:85], v[154:157], v[138:141], v[82:85]
	v_mfma_f32_16x16x32_bf16 v[86:89], v[154:157], v[142:145], v[86:89]
	ds_read_b128 v[150:153], v187 offset:10240
	s_cmpk_eq_i32 s10, 0x780
	s_cbranch_scc1 .Lg1_nodma2
	s_add_i32 m0, s17, 0x2000
	s_nop 0
	global_load_lds_dwordx4 v175, s[8:9]
.Lg1_nodma2:
	s_waitcnt lgkmcnt(2)
	v_mfma_f32_16x16x32_bf16 v[78:81], v[242:245], v[130:133], v[78:81]
	v_mfma_f32_16x16x32_bf16 v[74:77], v[242:245], v[134:137], v[74:77]
	v_mfma_f32_16x16x32_bf16 v[70:73], v[242:245], v[138:141], v[70:73]
	v_mfma_f32_16x16x32_bf16 v[66:69], v[242:245], v[142:145], v[66:69]
	ds_read_b128 v[154:157], v187 offset:12288
	ds_read_b128 v[198:201], v0 offset:33792
	s_cmpk_eq_i32 s10, 0x780
	s_cbranch_scc1 .Lg1_nodma3
	s_add_i32 m0, s17, 0xa000
	s_nop 0
	global_load_lds_dwordx4 v183, s[14:15]
.Lg1_nodma3:
	s_waitcnt lgkmcnt(3)
	v_mfma_f32_16x16x32_bf16 v[58:61], v[146:149], v[130:133], v[58:61]
	v_mfma_f32_16x16x32_bf16 v[54:57], v[146:149], v[134:137], v[54:57]
	v_mfma_f32_16x16x32_bf16 v[46:49], v[146:149], v[138:141], v[46:49]
	v_mfma_f32_16x16x32_bf16 v[50:53], v[146:149], v[142:145], v[50:53]
	ds_read_b128 v[242:245], v187 offset:14336
	ds_read_b128 v[202:205], v0 offset:35840
	s_cmpk_eq_i32 s10, 0x780
	s_cbranch_scc1 .Lg1_nodma4
	s_add_i32 m0, s17, 0x4000
	s_nop 0
	global_load_lds_dwordx4 v177, s[8:9]
.Lg1_nodma4:
	s_waitcnt lgkmcnt(4)
	v_mfma_f32_16x16x32_bf16 v[42:45], v[150:153], v[130:133], v[42:45]
	v_mfma_f32_16x16x32_bf16 v[38:41], v[150:153], v[134:137], v[38:41]
	v_mfma_f32_16x16x32_bf16 v[34:37], v[150:153], v[138:141], v[34:37]
	v_mfma_f32_16x16x32_bf16 v[30:33], v[150:153], v[142:145], v[30:33]
	ds_read_b128 v[146:149], v187 offset:1024
	ds_read_b128 v[206:209], v0 offset:37888
	s_cmpk_eq_i32 s10, 0x780
	s_cbranch_scc1 .Lg1_nodma5
	s_add_i32 m0, s17, 0xc000
	s_nop 0
	global_load_lds_dwordx4 v185, s[14:15]
.Lg1_nodma5:
	s_waitcnt lgkmcnt(5)
	v_mfma_f32_16x16x32_bf16 v[22:25], v[154:157], v[130:133], v[22:25]
	v_mfma_f32_16x16x32_bf16 v[18:21], v[154:157], v[134:137], v[18:21]
	v_mfma_f32_16x16x32_bf16 v[10:13], v[154:157], v[138:141], v[10:13]
	v_mfma_f32_16x16x32_bf16 v[14:17], v[154:157], v[142:145], v[14:17]
	ds_read_b128 v[150:153], v187 offset:3072
	ds_read_b128 v[210:213], v0 offset:39936
	s_cmpk_eq_i32 s10, 0x780
	s_cbranch_scc1 .Lg1_nodma6
	s_add_i32 m0, s17, 0x6000
	s_nop 0
	global_load_lds_dwordx4 v179, s[8:9]
.Lg1_nodma6:
	s_waitcnt lgkmcnt(5)
	v_mfma_f32_16x16x32_bf16 v[6:9], v[242:245], v[130:133], v[6:9]
	v_mfma_f32_16x16x32_bf16 v[2:5], v[242:245], v[134:137], v[2:5]
	v_mfma_f32_16x16x32_bf16 v[26:29], v[242:245], v[138:141], v[26:29]
	v_mfma_f32_16x16x32_bf16 v[62:65], v[242:245], v[142:145], v[62:65]
	ds_read_b128 v[154:157], v187 offset:5120
	s_cmpk_eq_i32 s10, 0x780
	s_cbranch_scc1 .Lg1_nodma7
	s_add_i32 m0, s17, 0xe000
	s_nop 0
	global_load_lds_dwordx4 v241, s[14:15]
.Lg1_nodma7:
	s_waitcnt lgkmcnt(1)
	v_mfma_f32_16x16x32_bf16 v[126:129], v[146:149], v[198:201], v[126:129]
	v_mfma_f32_16x16x32_bf16 v[122:125], v[146:149], v[202:205], v[122:125]
	v_mfma_f32_16x16x32_bf16 v[118:121], v[146:149], v[206:209], v[118:121]
	v_mfma_f32_16x16x32_bf16 v[114:117], v[146:149], v[210:213], v[114:117]
	ds_read_b128 v[242:245], v187 offset:7168
	v_mfma_f32_16x16x32_bf16 v[110:113], v[150:153], v[198:201], v[110:113]
	v_mfma_f32_16x16x32_bf16 v[106:109], v[150:153], v[202:205], v[106:109]
	v_mfma_f32_16x16x32_bf16 v[102:105], v[150:153], v[206:209], v[102:105]
	v_mfma_f32_16x16x32_bf16 v[98:101], v[150:153], v[210:213], v[98:101]
	ds_read_b128 v[146:149], v187 offset:9216
	s_waitcnt lgkmcnt(2)
	v_mfma_f32_16x16x32_bf16 v[94:97], v[154:157], v[198:201], v[94:97]
	v_mfma_f32_16x16x32_bf16 v[90:93], v[154:157], v[202:205], v[90:93]
	v_mfma_f32_16x16x32_bf16 v[82:85], v[154:157], v[206:209], v[82:85]
	v_mfma_f32_16x16x32_bf16 v[86:89], v[154:157], v[210:213], v[86:89]
	ds_read_b128 v[150:153], v187 offset:11264
	s_waitcnt lgkmcnt(2)
	v_mfma_f32_16x16x32_bf16 v[78:81], v[242:245], v[198:201], v[78:81]
	v_mfma_f32_16x16x32_bf16 v[74:77], v[242:245], v[202:205], v[74:77]
	v_mfma_f32_16x16x32_bf16 v[70:73], v[242:245], v[206:209], v[70:73]
	v_mfma_f32_16x16x32_bf16 v[66:69], v[242:245], v[210:213], v[66:69]
	ds_read_b128 v[154:157], v187 offset:13312
	s_waitcnt lgkmcnt(2)
	v_mfma_f32_16x16x32_bf16 v[58:61], v[146:149], v[198:201], v[58:61]
	v_mfma_f32_16x16x32_bf16 v[54:57], v[146:149], v[202:205], v[54:57]
	v_mfma_f32_16x16x32_bf16 v[46:49], v[146:149], v[206:209], v[46:49]
	v_mfma_f32_16x16x32_bf16 v[50:53], v[146:149], v[210:213], v[50:53]
	ds_read_b128 v[242:245], v187 offset:15360
	s_waitcnt lgkmcnt(2)
	v_mfma_f32_16x16x32_bf16 v[42:45], v[150:153], v[198:201], v[42:45]
	v_mfma_f32_16x16x32_bf16 v[38:41], v[150:153], v[202:205], v[38:41]
	v_mfma_f32_16x16x32_bf16 v[34:37], v[150:153], v[206:209], v[34:37]
	v_mfma_f32_16x16x32_bf16 v[30:33], v[150:153], v[210:213], v[30:33]
	s_waitcnt lgkmcnt(1)
	v_mfma_f32_16x16x32_bf16 v[22:25], v[154:157], v[198:201], v[22:25]
	v_mfma_f32_16x16x32_bf16 v[18:21], v[154:157], v[202:205], v[18:21]
	v_mfma_f32_16x16x32_bf16 v[10:13], v[154:157], v[206:209], v[10:13]
	v_mfma_f32_16x16x32_bf16 v[14:17], v[154:157], v[210:213], v[14:17]
	s_waitcnt vmcnt(0) lgkmcnt(0)
	s_barrier
	s_add_u32 s8, s8, 0x80
	s_addc_u32 s9, s9, 0
	s_add_u32 s14, s14, 0x80
	s_addc_u32 s15, s15, 0
	s_add_i32 s5, s5, 0x10000
	s_addk_i32 s10, 0x80
	s_cmpk_eq_i32 s10, 0x800
	s_cbranch_scc1 .Lg1_tail
	s_and_b32 s16, s5, 0x10000
	v_add3_u32 v187, s16, v171, v169
	v_add3_u32 v0, s16, v167, v169
	ds_read_b128 v[146:149], v187 offset:0
	ds_read_b128 v[130:133], v0 offset:32768
	ds_read_b128 v[134:137], v0 offset:34816
	ds_read_b128 v[138:141], v0 offset:36864
	ds_read_b128 v[142:145], v0 offset:38912
	ds_read_b128 v[150:153], v187 offset:2048
	ds_read_b128 v[154:157], v187 offset:4096
	s_xor_b32 s17, s16, 0x10000
	s_add_i32 s17, s17, s18
	v_mfma_f32_16x16x32_bf16 v[6:9], v[242:245], v[198:201], v[6:9]
	v_mfma_f32_16x16x32_bf16 v[2:5], v[242:245], v[202:205], v[2:5]
	v_mfma_f32_16x16x32_bf16 v[26:29], v[242:245], v[206:209], v[26:29]
	v_mfma_f32_16x16x32_bf16 v[62:65], v[242:245], v[210:213], v[62:65]
	s_branch .Lg1_loop
.Lg1_tail:
	v_mfma_f32_16x16x32_bf16 v[6:9], v[242:245], v[198:201], v[6:9]
	v_mfma_f32_16x16x32_bf16 v[2:5], v[242:245], v[202:205], v[2:5]
	v_mfma_f32_16x16x32_bf16 v[26:29], v[242:245], v[206:209], v[26:29]
	v_mfma_f32_16x16x32_bf16 v[62:65], v[242:245], v[210:213], v[62:65]

	.amdhsa_kernel _Z10fwd_kernel6Params
		.amdhsa_group_segment_fixed_size 147456
		.amdhsa_private_segment_fixed_size 0
		.amdhsa_kernarg_size 704
		.amdhsa_user_sgpr_count 2
		.amdhsa_user_sgpr_dispatch_ptr 0
		.amdhsa_user_sgpr_queue_ptr 0
		.amdhsa_user_sgpr_kernarg_segment_ptr 1
		.amdhsa_user_sgpr_dispatch_id 0
		.amdhsa_user_sgpr_kernarg_preload_length 0
		.amdhsa_user_sgpr_kernarg_preload_offset 0
		.amdhsa_user_sgpr_private_segment_size 0
		.amdhsa_uses_dynamic_stack 0
		.amdhsa_enable_private_segment 0
		.amdhsa_system_sgpr_workgroup_id_x 1
		.amdhsa_system_sgpr_workgroup_id_y 0
		.amdhsa_system_sgpr_workgroup_id_z 0
		.amdhsa_system_sgpr_workgroup_info 0
		.amdhsa_system_vgpr_workitem_id 2
		.amdhsa_next_free_vgpr 256
		.amdhsa_next_free_sgpr 100
		.amdhsa_accum_offset 256
		.amdhsa_reserve_vcc 1
		.amdhsa_float_round_mode_32 0
		.amdhsa_float_round_mode_16_64 0
		.amdhsa_float_denorm_mode_32 3
		.amdhsa_float_denorm_mode_16_64 3
		.amdhsa_dx10_clamp 1
		.amdhsa_ieee_mode 1
		.amdhsa_fp16_overflow 0
		.amdhsa_tg_split 0
		.amdhsa_exception_fp_ieee_invalid_op 0
		.amdhsa_exception_fp_denorm_src 0
		.amdhsa_exception_fp_ieee_div_zero 0
		.amdhsa_exception_fp_ieee_overflow 0
		.amdhsa_exception_fp_ieee_underflow 0
		.amdhsa_exception_fp_ieee_inexact 0
		.amdhsa_exception_int_div_zero 0
	.end_amdhsa_kernel

amdhsa.kernels:
  - .agpr_count:     0
    .args:
      - .offset:         0
        .size:           448
        .value_kind:     by_value
      - .offset:         448
        .size:           4
        .value_kind:     hidden_block_count_x
      - .offset:         452
        .size:           4
        .value_kind:     hidden_block_count_y
      - .offset:         456
        .size:           4
        .value_kind:     hidden_block_count_z
      - .offset:         460
        .size:           2
        .value_kind:     hidden_group_size_x
      - .offset:         462
        .size:           2
        .value_kind:     hidden_group_size_y
      - .offset:         464
        .size:           2
        .value_kind:     hidden_group_size_z
      - .offset:         466
        .size:           2
        .value_kind:     hidden_remainder_x
      - .offset:         468
        .size:           2
        .value_kind:     hidden_remainder_y
      - .offset:         470
        .size:           2
        .value_kind:     hidden_remainder_z
      - .offset:         488
        .size:           8
        .value_kind:     hidden_global_offset_x
      - .offset:         496
        .size:           8
        .value_kind:     hidden_global_offset_y
      - .offset:         504
        .size:           8
        .value_kind:     hidden_global_offset_z
      - .offset:         512
        .size:           2
        .value_kind:     hidden_grid_dims
      - .offset:         536
        .size:           8
        .value_kind:     hidden_multigrid_sync_arg
    .group_segment_fixed_size: 147456
    .kernarg_segment_align: 8
    .kernarg_segment_size: 704
    .language:       OpenCL C
    .language_version:
      - 2
      - 0
    .max_flat_workgroup_size: 512
    .name:           _Z10fwd_kernel6Params
    .private_segment_fixed_size: 0
    .sgpr_count:     106
    .sgpr_spill_count: 49
    .symbol:         _Z10fwd_kernel6Params.kd
    .uniform_work_group_size: 1
    .uses_dynamic_stack: false
    .vgpr_count:     256
    .vgpr_spill_count: 0
    .wavefront_size: 64
